# speedup vs baseline: 1.0110x; 1.0028x over previous
; __device__ __forceinline__ void p1_rows(const float* __restrict__ x, const float* __restrict__ ctx, const float* __restrict__ mod,
;                                         u16* __restrict__ H, u16* __restrict__ Hc) {
;     ...
;   for (int row = blockIdx.x * 8 + wid; row < nrows; row += gridDim.x * 8) {
;     const float* src; u16* dst; int b;
;     if (row < TT) { src = x + (size_t)row * DM; dst = H + (size_t)row * DM; b = row >> 12; }
;     else { int r2 = row - TT; src = ctx + (size_t)r2 * DM; dst = Hc + (size_t)r2 * DM; b = 8; }
;     f32x4 v[8]; float ss = 0.f;
; #pragma unroll
;     for (int i = 0; i < 8; ++i) { v[i] = *reinterpret_cast<const f32x4*>(src + (i * 64 + lane) * 4); ss += v[i][0] * v[i][0] + v[i][1] * v[i][1] + v[i][2] * v[i][2] + v[i][3] * v[i][3]; }
;     ss = wave_sum(ss);
;     const float rstd = rsqrtf(ss * (1.f / DM) + 1e-6f);
;     const float* sh = mod + b * 6144; const float* scl = sh + 2048;
; #pragma unroll
;     for (int i = 0; i < 8; ++i) {
;       const int cidx = (i * 64 + lane) * 4;
;       const f32x4 s4 = *reinterpret_cast<const f32x4*>(sh + cidx), c4 = *reinterpret_cast<const f32x4*>(scl + cidx);
;       float o0 = v[i][0] * rstd * (1.f + c4[0]) + s4[0], o1 = v[i][1] * rstd * (1.f + c4[1]) + s4[1];
;       float o2 = v[i][2] * rstd * (1.f + c4[2]) + s4[2], o3 = v[i][3] * rstd * (1.f + c4[3]) + s4[3];
;       u32x2 w = { cvtpk(o0, o1), cvtpk(o2, o3) };
;       *reinterpret_cast<u32x2*>(dst + cidx) = w;
;     }
.LBB0_131:
	s_or_b64 exec, exec, s[18:19]
	v_lshl_add_u64 v[4:5], v[2:3], 0, v[42:43]
	global_load_dwordx4 v[58:61], v[4:5], off
	global_load_dwordx4 v[62:65], v[4:5], off offset:1024
	global_load_dwordx4 v[22:25], v[4:5], off offset:2048
	global_load_dwordx4 v[18:21], v[4:5], off offset:3072
	v_lshl_add_u64 v[4:5], v[2:3], 0, v[30:31]
	v_lshl_add_u64 v[6:7], v[2:3], 0, v[32:33]
	global_load_dwordx4 v[14:17], v[4:5], off
	global_load_dwordx4 v[10:13], v[6:7], off
	v_lshl_add_u64 v[48:49], v[2:3], 0, v[34:35]
	v_lshl_add_u64 v[66:67], v[2:3], 0, v[36:37]
	global_load_dwordx4 v[6:9], v[48:49], off
	global_load_dwordx4 v[2:5], v[66:67], off
	v_lshl_add_u64 v[46:47], v[46:47], 2, s[26:27]
	v_lshl_add_u64 v[48:49], v[46:47], 0, s[16:17]
	v_lshl_add_u64 v[74:75], v[46:47], 0, v[42:43]
	v_lshl_add_u64 v[76:77], v[48:49], 0, v[42:43]
	global_load_dwordx4 v[66:69], v[74:75], off
	global_load_dwordx4 v[70:73], v[76:77], off
	v_lshl_add_u64 v[50:51], v[50:51], 0, v[44:45]
	v_add_u32_e32 v26, s3, v26
	s_waitcnt vmcnt(9)
	v_mul_f32_e32 v27, v59, v59
	s_waitcnt vmcnt(8)
	v_mul_f32_e32 v92, v63, v63
	s_waitcnt vmcnt(7)
	v_mul_f32_e32 v93, v23, v23
	v_fmac_f32_e32 v27, v58, v58
	v_fmac_f32_e32 v92, v62, v62
	s_waitcnt vmcnt(6)
	v_mul_f32_e32 v94, v19, v19
	s_waitcnt vmcnt(5)
	v_mov_b32_e32 v78, v15
	s_waitcnt vmcnt(4)
	v_mov_b32_e32 v79, v11
	v_fmac_f32_e32 v93, v22, v22
	v_fmac_f32_e32 v27, v60, v60
	v_fmac_f32_e32 v92, v64, v64
	v_mov_b32_e32 v76, v14
	v_mov_b32_e32 v77, v10
	v_fmac_f32_e32 v94, v18, v18
	v_pk_mul_f32 v[78:79], v[78:79], v[78:79]
	v_fmac_f32_e32 v93, v24, v24
	v_fmac_f32_e32 v27, v61, v61
	v_fmac_f32_e32 v92, v65, v65
	v_mov_b32_e32 v80, v16
	v_mov_b32_e32 v81, v12
	s_waitcnt vmcnt(3)
	v_mov_b32_e32 v86, v7
	s_waitcnt vmcnt(2)
	v_mov_b32_e32 v87, v3
	v_fmac_f32_e32 v94, v20, v20
	v_pk_fma_f32 v[76:77], v[76:77], v[76:77], v[78:79]
	v_fmac_f32_e32 v93, v25, v25
	v_add_f32_e32 v27, v27, v92
	v_mov_b32_e32 v82, v17
	v_mov_b32_e32 v83, v13
	v_mov_b32_e32 v84, v6
	v_mov_b32_e32 v85, v2
	v_pk_mul_f32 v[86:87], v[86:87], v[86:87]
	v_fmac_f32_e32 v94, v21, v21
	v_pk_fma_f32 v[76:77], v[80:81], v[80:81], v[76:77]
	v_add_f32_e32 v27, v27, v93
	v_mov_b32_e32 v88, v8
	v_mov_b32_e32 v89, v4
	v_pk_fma_f32 v[78:79], v[84:85], v[84:85], v[86:87]
	v_pk_fma_f32 v[76:77], v[82:83], v[82:83], v[76:77]
	v_add_f32_e32 v27, v27, v94
	v_mov_b32_e32 v90, v9
	v_mov_b32_e32 v91, v5
	v_pk_fma_f32 v[78:79], v[88:89], v[88:89], v[78:79]
	v_add_f32_e32 v27, v27, v76
	v_pk_fma_f32 v[78:79], v[90:91], v[90:91], v[78:79]
	v_add_f32_e32 v27, v27, v77
	v_add_f32_e32 v27, v27, v78
	v_add_f32_e32 v27, v27, v79
	ds_bpermute_b32 v76, v1, v27
	s_waitcnt vmcnt(0)
	v_add_f32_e32 v70, 1.0, v70
	v_add_f32_e32 v71, 1.0, v71
	v_add_f32_e32 v72, 1.0, v72
	v_add_f32_e32 v73, 1.0, v73
	s_waitcnt lgkmcnt(0)
	v_add_f32_e32 v27, v27, v76
	ds_bpermute_b32 v76, v52, v27
	s_waitcnt lgkmcnt(0)
	v_add_f32_e32 v27, v27, v76
	s_nop 1
	v_mov_b32_dpp v76, v27 row_ror:8 row_mask:0xf bank_mask:0xf
	s_waitcnt lgkmcnt(0)
	v_add_f32_e32 v27, v27, v76
	s_nop 1
	v_mov_b32_dpp v76, v27 row_ror:4 row_mask:0xf bank_mask:0xf
	s_waitcnt lgkmcnt(0)
	v_add_f32_e32 v27, v27, v76
	s_nop 1
	v_mov_b32_dpp v76, v27 quad_perm:[2,3,0,1] row_mask:0xf bank_mask:0xf
	s_waitcnt lgkmcnt(0)
	v_add_f32_e32 v27, v27, v76
	s_nop 1
	v_mov_b32_dpp v78, v27 quad_perm:[1,0,3,2] row_mask:0xf bank_mask:0xf
	v_lshl_add_u64 v[76:77], v[48:49], 0, v[28:29]
	s_waitcnt lgkmcnt(0)
	v_add_f32_e32 v27, v27, v78
	v_fmamk_f32 v27, v27, 0x3a000000, v57
	v_mul_f32_e32 v78, 0x4b800000, v27
	v_cmp_gt_f32_e32 vcc, s21, v27
	s_nop 1
	v_cndmask_b32_e32 v27, v27, v78, vcc
	v_rsq_f32_e32 v27, v27
	s_nop 0
	v_mul_f32_e32 v78, 0x45800000, v27
	v_cndmask_b32_e32 v27, v27, v78, vcc
	v_mul_f32_e32 v58, v58, v27
	v_mul_f32_e32 v59, v59, v27
	v_mul_f32_e32 v60, v60, v27
	v_mul_f32_e32 v61, v61, v27
	v_fma_f32 v58, v70, v58, v66
	v_fma_f32 v59, v71, v59, v67
	v_fma_f32 v60, v72, v60, v68
	v_fmac_f32_e32 v69, v73, v61
	s_nop 0
	v_cvt_pk_bf16_f32 v70, v58, v59
	s_nop 0
	v_cvt_pk_bf16_f32 v71, v60, v69
	global_load_dwordx4 v[58:61], v[76:77], off
	global_load_dwordx4 v[66:69], v[74:75], off offset:1024
	v_mul_f32_e32 v62, v62, v27
	v_mul_f32_e32 v63, v63, v27
	v_mul_f32_e32 v64, v64, v27
	v_lshl_add_u64 v[72:73], v[48:49], 0, v[38:39]
	v_mul_f32_e32 v65, v65, v27
	global_store_dwordx2 v[50:51], v[70:71], off
	v_mul_f32_e32 v22, v22, v27
	v_mul_f32_e32 v23, v23, v27
	v_mul_f32_e32 v24, v24, v27
	v_mul_f32_e32 v25, v25, v27
	v_mul_f32_e32 v18, v18, v27
	v_mul_f32_e32 v19, v19, v27
	v_mul_f32_e32 v20, v20, v27
	v_mul_f32_e32 v21, v21, v27
	v_mul_f32_e32 v14, v14, v27
	v_mul_f32_e32 v15, v15, v27
	v_mul_f32_e32 v16, v16, v27
	v_mul_f32_e32 v17, v17, v27
	v_mul_f32_e32 v10, v10, v27
	v_mul_f32_e32 v11, v11, v27
	v_mul_f32_e32 v12, v12, v27
	v_mul_f32_e32 v13, v13, v27
	v_mul_f32_e32 v6, v6, v27
	v_mul_f32_e32 v7, v7, v27
	v_mul_f32_e32 v8, v8, v27
	v_mul_f32_e32 v9, v9, v27
	v_cmp_lt_i32_e32 vcc, s30, v26
	v_mul_f32_e32 v2, v2, v27
	v_mul_f32_e32 v3, v3, v27
	v_mul_f32_e32 v4, v4, v27
	v_mul_f32_e32 v5, v5, v27
	s_or_b64 s[12:13], vcc, s[12:13]
	s_waitcnt vmcnt(2)
; __device__ __forceinline__ void p1_rows(const float* __restrict__ x, const float* __restrict__ ctx, const float* __restrict__ mod,
;                                         u16* __restrict__ H, u16* __restrict__ Hc) {
;     ...
; #pragma unroll
;     for (int i = 0; i < 8; ++i) {
;       const int cidx = (i * 64 + lane) * 4;
;       const f32x4 s4 = *reinterpret_cast<const f32x4*>(sh + cidx), c4 = *reinterpret_cast<const f32x4*>(scl + cidx);
;       float o0 = v[i][0] * rstd * (1.f + c4[0]) + s4[0], o1 = v[i][1] * rstd * (1.f + c4[1]) + s4[1];
;       float o2 = v[i][2] * rstd * (1.f + c4[2]) + s4[2], o3 = v[i][3] * rstd * (1.f + c4[3]) + s4[3];
;       u32x2 w = { cvtpk(o0, o1), cvtpk(o2, o3) };
;       *reinterpret_cast<u32x2*>(dst + cidx) = w;
;     }
	v_add_f32_e32 v58, 1.0, v58
	v_add_f32_e32 v59, 1.0, v59
	v_add_f32_e32 v60, 1.0, v60
	v_add_f32_e32 v61, 1.0, v61
	s_waitcnt vmcnt(1)
	v_fma_f32 v58, v58, v62, v66
	v_fma_f32 v59, v59, v63, v67
	v_fma_f32 v60, v60, v64, v68
	v_fmac_f32_e32 v69, v61, v65
	s_nop 0
	v_cvt_pk_bf16_f32 v66, v58, v59
	s_nop 0
	v_cvt_pk_bf16_f32 v67, v60, v69
	global_load_dwordx4 v[58:61], v[72:73], off
	global_load_dwordx4 v[62:65], v[74:75], off offset:2048
	v_lshl_add_u64 v[68:69], v[48:49], 0, v[40:41]
	global_store_dwordx2 v[50:51], v[66:67], off offset:512
	s_waitcnt vmcnt(2)
	v_add_f32_e32 v58, 1.0, v58
	v_add_f32_e32 v59, 1.0, v59
	v_add_f32_e32 v60, 1.0, v60
	v_add_f32_e32 v61, 1.0, v61
	s_waitcnt vmcnt(1)
	v_fma_f32 v22, v22, v58, v62
	v_fma_f32 v23, v23, v59, v63
	v_fma_f32 v24, v24, v60, v64
	v_fmac_f32_e32 v65, v25, v61
	s_nop 0
	v_cvt_pk_bf16_f32 v62, v22, v23
	s_nop 0
	v_cvt_pk_bf16_f32 v63, v24, v65
	global_load_dwordx4 v[22:25], v[68:69], off
	global_load_dwordx4 v[58:61], v[74:75], off offset:3072
	v_lshl_add_u64 v[64:65], v[48:49], 0, v[30:31]
	global_store_dwordx2 v[50:51], v[62:63], off offset:1024
	s_waitcnt vmcnt(2)
	v_add_f32_e32 v22, 1.0, v22
	v_add_f32_e32 v23, 1.0, v23
	v_add_f32_e32 v24, 1.0, v24
	v_add_f32_e32 v25, 1.0, v25
	s_waitcnt vmcnt(1)
	v_fma_f32 v18, v18, v22, v58
	v_fma_f32 v19, v19, v23, v59
	v_fma_f32 v20, v20, v24, v60
	v_fmac_f32_e32 v61, v21, v25
	s_nop 0
	v_cvt_pk_bf16_f32 v58, v18, v19
	s_nop 0
	v_cvt_pk_bf16_f32 v59, v20, v61
	global_load_dwordx4 v[18:21], v[64:65], off
	v_lshl_add_u64 v[22:23], v[46:47], 0, v[30:31]
	global_load_dwordx4 v[22:25], v[22:23], off
	v_lshl_add_u64 v[60:61], v[48:49], 0, v[32:33]
	global_store_dwordx2 v[50:51], v[58:59], off offset:1536
	s_waitcnt vmcnt(2)
	v_add_f32_e32 v18, 1.0, v18
	v_add_f32_e32 v19, 1.0, v19
	v_add_f32_e32 v20, 1.0, v20
	v_add_f32_e32 v21, 1.0, v21
	s_waitcnt vmcnt(1)
	v_fma_f32 v14, v14, v18, v22
	v_fma_f32 v15, v15, v19, v23
	v_fma_f32 v16, v16, v20, v24
	v_fmac_f32_e32 v25, v17, v21
	s_nop 0
	v_cvt_pk_bf16_f32 v22, v14, v15
	s_nop 0
	v_cvt_pk_bf16_f32 v23, v16, v25
	global_load_dwordx4 v[14:17], v[60:61], off
	v_lshl_add_u64 v[18:19], v[46:47], 0, v[32:33]
	global_load_dwordx4 v[18:21], v[18:19], off
	v_lshl_add_u64 v[24:25], v[48:49], 0, v[34:35]
	global_store_dwordx2 v[50:51], v[22:23], off offset:2048
	s_waitcnt vmcnt(2)
	v_add_f32_e32 v14, 1.0, v14
	v_add_f32_e32 v15, 1.0, v15
	v_add_f32_e32 v16, 1.0, v16
	v_add_f32_e32 v17, 1.0, v17
	s_waitcnt vmcnt(1)
	v_fma_f32 v10, v10, v14, v18
	v_fma_f32 v11, v11, v15, v19
	v_fma_f32 v12, v12, v16, v20
	v_fmac_f32_e32 v21, v13, v17
	s_nop 0
	v_cvt_pk_bf16_f32 v18, v10, v11
	s_nop 0
	v_cvt_pk_bf16_f32 v19, v12, v21
	global_load_dwordx4 v[10:13], v[24:25], off
	v_lshl_add_u64 v[14:15], v[46:47], 0, v[34:35]
	global_load_dwordx4 v[14:17], v[14:15], off
	v_lshl_add_u64 v[20:21], v[48:49], 0, v[36:37]
	global_store_dwordx2 v[50:51], v[18:19], off offset:2560
	s_waitcnt vmcnt(2)
	v_add_f32_e32 v10, 1.0, v10
	v_add_f32_e32 v11, 1.0, v11
	v_add_f32_e32 v12, 1.0, v12
	v_add_f32_e32 v13, 1.0, v13
	s_waitcnt vmcnt(1)
	v_fma_f32 v6, v6, v10, v14
	v_fma_f32 v7, v7, v11, v15
	v_fma_f32 v8, v8, v12, v16
	v_fmac_f32_e32 v17, v9, v13
	s_nop 0
	v_cvt_pk_bf16_f32 v14, v6, v7
	s_nop 0
	v_cvt_pk_bf16_f32 v15, v8, v17
	global_load_dwordx4 v[6:9], v[20:21], off
	v_lshl_add_u64 v[10:11], v[46:47], 0, v[36:37]
	global_load_dwordx4 v[10:13], v[10:11], off
	s_waitcnt vmcnt(1)
	v_add_f32_e32 v6, 1.0, v6
	v_add_f32_e32 v7, 1.0, v7
	v_add_f32_e32 v8, 1.0, v8
	v_add_f32_e32 v9, 1.0, v9
	s_waitcnt vmcnt(0)
	v_fma_f32 v2, v2, v6, v10
	v_fma_f32 v3, v3, v7, v11
	global_store_dwordx2 v[50:51], v[14:15], off offset:3072
	v_fma_f32 v4, v4, v8, v12
	v_fmac_f32_e32 v13, v5, v9
	s_nop 0
	v_cvt_pk_bf16_f32 v2, v2, v3
	s_nop 0
	v_cvt_pk_bf16_f32 v3, v4, v13
	global_store_dwordx2 v[50:51], v[2:3], off offset:3584
	s_andn2_b64 exec, exec, s[12:13]
	s_cbranch_execz .LBB0_136

; __device__ __forceinline__ float bflo(unsigned v) { return __uint_as_float(v << 16); }
; __device__ __forceinline__ float bfhi(unsigned v) { return __uint_as_float(v & 0xffff0000u); }
; __device__ __forceinline__ void p6_rows(const float* __restrict__ x, const u16* __restrict__ Mm, const float* __restrict__ mod,
;                                         const float* __restrict__ fnw, float* __restrict__ out) {
;     ...
;   for (int row = blockIdx.x * 8 + wid; row < TT; row += gridDim.x * 8) {
;     const float* xs = x + (size_t)row * DM; const u16* ms = Mm + (size_t)row * DM; float* dst = out + (size_t)row * DM;
;     const float* gate = mod + (row >> 12) * 6144 + 4096;
;     f32x4 v[8]; u32x2 mv[8]; float ss = 0.f;
; #pragma unroll
;     for (int i = 0; i < 8; ++i) { v[i] = *reinterpret_cast<const f32x4*>(xs + (i * 64 + lane) * 4); mv[i] = *reinterpret_cast<const u32x2*>(ms + (i * 64 + lane) * 4); }
; #pragma unroll
;     for (int i = 0; i < 8; ++i) {
;       const f32x4 g4 = *reinterpret_cast<const f32x4*>(gate + (i * 64 + lane) * 4);
;       v[i][0] += g4[0] * bflo(mv[i][0]); v[i][1] += g4[1] * bfhi(mv[i][0]); v[i][2] += g4[2] * bflo(mv[i][1]); v[i][3] += g4[3] * bfhi(mv[i][1]);
;       ss += v[i][0] * v[i][0] + v[i][1] * v[i][1] + v[i][2] * v[i][2] + v[i][3] * v[i][3];
;     }
.LBB0_566:
	v_ashrrev_i32_e32 v187, 31, v186
	v_ashrrev_i32_e32 v37, 12, v186
	v_lshlrev_b64 v[60:61], 12, v[186:187]
	v_lshl_add_u64 v[118:119], v[34:35], 0, v[60:61]
	v_mul_i32_i24_e32 v60, 0x1800, v37
	v_ashrrev_i32_e32 v61, 31, v60
	v_lshlrev_b64 v[50:51], 13, v[186:187]
	v_lshl_add_u64 v[76:77], v[60:61], 2, s[26:27]
	s_waitcnt lgkmcnt(0)
	v_lshl_add_u64 v[116:117], s[36:37], 0, v[50:51]
	v_lshl_add_u64 v[120:121], v[76:77], 0, s[2:3]
	global_load_dwordx2 v[124:125], v[118:119], off
	global_load_dwordx2 v[126:127], v[118:119], off offset:512
	v_lshl_add_u64 v[78:79], v[116:117], 0, v[32:33]
	v_lshl_add_u64 v[84:85], v[120:121], 0, v[32:33]
	v_mov_b32_e32 v45, v33
	v_mov_b32_e32 v37, v33
	global_load_dwordx4 v[60:63], v[78:79], off
	global_load_dwordx4 v[64:67], v[78:79], off offset:1024
	global_load_dwordx2 v[128:129], v[118:119], off offset:1024
	global_load_dwordx4 v[68:71], v[78:79], off offset:2048
	global_load_dwordx4 v[72:75], v[78:79], off offset:3072
	global_load_dwordx2 v[130:131], v[118:119], off offset:1536
	global_load_dwordx2 v[132:133], v[118:119], off offset:2048
	v_lshl_add_u64 v[86:87], v[120:121], 0, v[44:45]
	global_load_dwordx4 v[76:79], v[84:85], off
	global_load_dwordx4 v[80:83], v[86:87], off
	v_mov_b32_e32 v47, v33
	v_mov_b32_e32 v49, v33
	v_lshl_add_u64 v[92:93], v[116:117], 0, v[36:37]
	v_lshl_add_u64 v[96:97], v[120:121], 0, v[36:37]
	v_mov_b32_e32 v39, v33
	v_lshl_add_u64 v[84:85], v[120:121], 0, v[46:47]
	v_lshl_add_u64 v[88:89], v[120:121], 0, v[48:49]
	global_load_dwordx4 v[92:95], v[92:93], off
	v_lshl_add_u64 v[104:105], v[116:117], 0, v[38:39]
	global_load_dwordx4 v[96:99], v[96:97], off
	v_mov_b32_e32 v41, v33
	global_load_dwordx4 v[84:87], v[84:85], off
	v_mov_b32_e32 v43, v33
	global_load_dwordx4 v[88:91], v[88:89], off
	s_nop 0
	global_load_dwordx2 v[134:135], v[118:119], off offset:2560
	global_load_dwordx4 v[100:103], v[104:105], off
	v_lshl_add_u64 v[104:105], v[120:121], 0, v[38:39]
	global_load_dwordx4 v[104:107], v[104:105], off
	v_lshl_add_u64 v[108:109], v[116:117], 0, v[40:41]
	v_lshl_add_u64 v[112:113], v[120:121], 0, v[40:41]
	v_lshl_add_u64 v[116:117], v[116:117], 0, v[42:43]
	v_lshl_add_u64 v[120:121], v[120:121], 0, v[42:43]
	global_load_dwordx2 v[136:137], v[118:119], off offset:3072
	s_nop 0
	global_load_dwordx4 v[108:111], v[108:109], off
	v_lshl_add_u64 v[50:51], s[24:25], 0, v[50:51]
	global_load_dwordx4 v[112:115], v[112:113], off
	s_nop 0
	global_load_dwordx2 v[138:139], v[118:119], off offset:3584
	s_nop 0
	global_load_dwordx4 v[116:119], v[116:117], off
	v_add_u32_e32 v186, s4, v186
	global_load_dwordx4 v[120:123], v[120:121], off
	s_waitcnt vmcnt(23)
	v_lshlrev_b32_e32 v140, 16, v124
	v_and_b32_e32 v141, 0xffff0000, v124
	s_waitcnt vmcnt(22)
	v_lshlrev_b32_e32 v142, 16, v126
	v_and_b32_e32 v143, 0xffff0000, v126
	v_lshlrev_b32_e32 v124, 16, v125
	v_and_b32_e32 v125, 0xffff0000, v125
	v_lshlrev_b32_e32 v126, 16, v127
	v_and_b32_e32 v127, 0xffff0000, v127
	s_waitcnt vmcnt(15)
	v_lshlrev_b32_e32 v148, 16, v132
	v_and_b32_e32 v149, 0xffff0000, v132
	s_waitcnt vmcnt(14)
	v_pk_fma_f32 v[60:61], v[76:77], v[140:141], v[60:61]
	s_waitcnt vmcnt(13)
	v_pk_fma_f32 v[64:65], v[80:81], v[142:143], v[64:65]
	v_pk_fma_f32 v[62:63], v[78:79], v[124:125], v[62:63]
	v_pk_fma_f32 v[66:67], v[82:83], v[126:127], v[66:67]
	v_pk_mul_f32 v[76:77], v[60:61], v[60:61]
	v_pk_mul_f32 v[80:81], v[64:65], v[64:65]
	v_lshlrev_b32_e32 v144, 16, v128
	v_and_b32_e32 v145, 0xffff0000, v128
	s_waitcnt vmcnt(11)
	v_pk_fma_f32 v[92:93], v[96:97], v[148:149], v[92:93]
	v_lshlrev_b32_e32 v96, 16, v133
	v_and_b32_e32 v97, 0xffff0000, v133
	v_pk_mul_f32 v[78:79], v[62:63], v[62:63]
	v_pk_mul_f32 v[82:83], v[66:67], v[66:67]
	v_pk_fma_f32 v[94:95], v[98:99], v[96:97], v[94:95]
	s_waitcnt vmcnt(8)
	v_lshlrev_b32_e32 v96, 16, v134
	v_and_b32_e32 v97, 0xffff0000, v134
	v_add_f32_e32 v45, v80, v81
	v_add_f32_e32 v47, v76, v77
	v_lshlrev_b32_e32 v128, 16, v129
	v_and_b32_e32 v129, 0xffff0000, v129
	v_pk_fma_f32 v[68:69], v[84:85], v[144:145], v[68:69]
	s_waitcnt vmcnt(6)
	v_pk_fma_f32 v[96:97], v[104:105], v[96:97], v[100:101]
	v_lshlrev_b32_e32 v98, 16, v135
	v_and_b32_e32 v99, 0xffff0000, v135
	v_add_f32_e32 v45, v82, v45
	v_add_f32_e32 v47, v78, v47
	v_pk_fma_f32 v[70:71], v[86:87], v[128:129], v[70:71]
	v_pk_mul_f32 v[84:85], v[68:69], v[68:69]
	v_pk_fma_f32 v[98:99], v[106:107], v[98:99], v[102:103]
	v_mov_b32_e32 v102, v93
	v_mov_b32_e32 v103, v97
	v_add_f32_e32 v45, v83, v45
	v_add_f32_e32 v47, v79, v47
	v_lshlrev_b32_e32 v146, 16, v130
	v_and_b32_e32 v147, 0xffff0000, v130
	v_pk_mul_f32 v[86:87], v[70:71], v[70:71]
	v_mov_b32_e32 v100, v92
	v_mov_b32_e32 v101, v96
	v_pk_mul_f32 v[102:103], v[102:103], v[102:103]
	v_add_f32_e32 v45, v47, v45
	v_add_f32_e32 v47, v84, v85
	v_lshlrev_b32_e32 v130, 16, v131
	v_and_b32_e32 v131, 0xffff0000, v131
	v_pk_fma_f32 v[72:73], v[88:89], v[146:147], v[72:73]
	v_pk_fma_f32 v[100:101], v[100:101], v[100:101], v[102:103]
	v_mov_b32_e32 v102, v94
	v_mov_b32_e32 v103, v98
	v_add_f32_e32 v47, v86, v47
	v_pk_fma_f32 v[74:75], v[90:91], v[130:131], v[74:75]
	v_pk_mul_f32 v[88:89], v[72:73], v[72:73]
	v_pk_fma_f32 v[100:101], v[102:103], v[102:103], v[100:101]
	s_waitcnt vmcnt(5)
; __device__ __forceinline__ void p6_rows(const float* __restrict__ x, const u16* __restrict__ Mm, const float* __restrict__ mod,
;                                         const float* __restrict__ fnw, float* __restrict__ out) {
;     ...
;       ss += v[i][0] * v[i][0] + v[i][1] * v[i][1] + v[i][2] * v[i][2] + v[i][3] * v[i][3];
;     }
;     ss = wave_sum(ss);
;     const float rstd = rsqrtf(ss * (1.f / DM) + 1e-6f);
; #pragma unroll
;     for (int i = 0; i < 8; ++i) {
;       const int cidx = (i * 64 + lane) * 4;
;       const f32x4 w4 = *reinterpret_cast<const f32x4*>(fnw + cidx);
;       f32x4 o = { v[i][0] * rstd * w4[0], v[i][1] * rstd * w4[1], v[i][2] * rstd * w4[2], v[i][3] * rstd * w4[3] };
;       *reinterpret_cast<f32x4*>(dst + cidx) = o;
;     }
	v_lshlrev_b32_e32 v102, 16, v136
	v_and_b32_e32 v103, 0xffff0000, v136
	s_waitcnt vmcnt(2)
	v_lshlrev_b32_e32 v106, 16, v138
	v_and_b32_e32 v107, 0xffff0000, v138
	v_add_f32_e32 v47, v87, v47
	v_pk_mul_f32 v[90:91], v[74:75], v[74:75]
	v_mov_b32_e32 v104, v95
	v_mov_b32_e32 v105, v99
	v_pk_fma_f32 v[102:103], v[112:113], v[102:103], v[108:109]
	s_waitcnt vmcnt(0)
	v_pk_fma_f32 v[106:107], v[120:121], v[106:107], v[116:117]
	v_add_f32_e32 v45, v45, v47
	v_add_f32_e32 v47, v88, v89
	v_pk_fma_f32 v[100:101], v[104:105], v[104:105], v[100:101]
	v_lshlrev_b32_e32 v104, 16, v137
	v_and_b32_e32 v105, 0xffff0000, v137
	v_lshlrev_b32_e32 v108, 16, v139
	v_and_b32_e32 v109, 0xffff0000, v139
	v_mov_b32_e32 v112, v103
	v_mov_b32_e32 v113, v107
	v_add_f32_e32 v47, v90, v47
	v_pk_fma_f32 v[104:105], v[114:115], v[104:105], v[110:111]
	v_pk_fma_f32 v[108:109], v[122:123], v[108:109], v[118:119]
	v_mov_b32_e32 v110, v102
	v_mov_b32_e32 v111, v106
	v_pk_mul_f32 v[112:113], v[112:113], v[112:113]
	v_add_f32_e32 v47, v91, v47
	v_pk_fma_f32 v[110:111], v[110:111], v[110:111], v[112:113]
	v_mov_b32_e32 v112, v104
	v_mov_b32_e32 v113, v108
	v_add_f32_e32 v45, v45, v47
	v_mov_b32_e32 v114, v105
	v_mov_b32_e32 v115, v109
	v_pk_fma_f32 v[110:111], v[112:113], v[112:113], v[110:111]
	v_add_f32_e32 v45, v45, v100
	v_pk_fma_f32 v[110:111], v[114:115], v[114:115], v[110:111]
	v_add_f32_e32 v45, v45, v101
	v_add_f32_e32 v45, v45, v110
	v_add_f32_e32 v45, v45, v111
	ds_bpermute_b32 v47, v52, v45
	v_lshl_add_u64 v[78:79], v[50:51], 0, v[36:37]
	v_lshl_add_u64 v[76:77], v[50:51], 0, v[32:33]
	v_lshl_add_u64 v[80:81], v[50:51], 0, v[38:39]
	v_lshl_add_u64 v[82:83], v[50:51], 0, v[40:41]
	s_waitcnt lgkmcnt(0)
	v_add_f32_e32 v45, v45, v47
	ds_bpermute_b32 v47, v53, v45
	v_lshl_add_u64 v[50:51], v[50:51], 0, v[42:43]
	s_waitcnt lgkmcnt(0)
	v_add_f32_e32 v45, v45, v47
	s_nop 1
	v_mov_b32_dpp v47, v45 row_ror:8 row_mask:0xf bank_mask:0xf
	s_waitcnt lgkmcnt(0)
	v_add_f32_e32 v45, v45, v47
	s_nop 1
	v_mov_b32_dpp v47, v45 row_ror:4 row_mask:0xf bank_mask:0xf
	s_waitcnt lgkmcnt(0)
	v_add_f32_e32 v45, v45, v47
	s_nop 1
	v_mov_b32_dpp v47, v45 quad_perm:[2,3,0,1] row_mask:0xf bank_mask:0xf
	s_waitcnt lgkmcnt(0)
	v_add_f32_e32 v45, v45, v47
	s_nop 1
	v_mov_b32_dpp v47, v45 quad_perm:[1,0,3,2] row_mask:0xf bank_mask:0xf
	s_waitcnt lgkmcnt(0)
	v_add_f32_e32 v45, v45, v47
	v_fmamk_f32 v45, v45, 0x3a000000, v58
	v_mul_f32_e32 v47, 0x4b800000, v45
	v_cmp_gt_f32_e32 vcc, s5, v45
	s_nop 1
	v_cndmask_b32_e32 v45, v45, v47, vcc
	v_rsq_f32_e32 v45, v45
	s_nop 0
	v_mul_f32_e32 v37, 0x45800000, v45
	v_cndmask_b32_e32 v84, v45, v37, vcc
	v_pk_mul_f32 v[60:61], v[60:61], v[84:85] op_sel_hi:[1,0]
	v_pk_mul_f32 v[62:63], v[62:63], v[84:85] op_sel_hi:[1,0]
	v_pk_mul_f32 v[60:61], v[0:1], v[60:61]
	v_pk_mul_f32 v[62:63], v[2:3], v[62:63]
	global_store_dwordx4 v[76:77], v[60:63], off
	v_cmp_lt_i32_e32 vcc, s6, v186
	s_or_b64 s[0:1], vcc, s[0:1]
	v_pk_mul_f32 v[60:61], v[64:65], v[84:85] op_sel_hi:[1,0]
	v_pk_mul_f32 v[62:63], v[66:67], v[84:85] op_sel_hi:[1,0]
	v_pk_mul_f32 v[60:61], v[4:5], v[60:61]
	v_pk_mul_f32 v[62:63], v[6:7], v[62:63]
	global_store_dwordx4 v[76:77], v[60:63], off offset:1024
	s_nop 1
	v_pk_mul_f32 v[60:61], v[68:69], v[84:85] op_sel_hi:[1,0]
	v_pk_mul_f32 v[62:63], v[70:71], v[84:85] op_sel_hi:[1,0]
	v_pk_mul_f32 v[60:61], v[8:9], v[60:61]
	v_pk_mul_f32 v[62:63], v[10:11], v[62:63]
	global_store_dwordx4 v[76:77], v[60:63], off offset:2048
	s_nop 1
	v_pk_mul_f32 v[60:61], v[72:73], v[84:85] op_sel_hi:[1,0]
	v_pk_mul_f32 v[62:63], v[74:75], v[84:85] op_sel_hi:[1,0]
	v_pk_mul_f32 v[60:61], v[12:13], v[60:61]
	v_pk_mul_f32 v[62:63], v[14:15], v[62:63]
	global_store_dwordx4 v[76:77], v[60:63], off offset:3072
	s_nop 1
	v_pk_mul_f32 v[60:61], v[92:93], v[84:85] op_sel_hi:[1,0]
	v_pk_mul_f32 v[62:63], v[94:95], v[84:85] op_sel_hi:[1,0]
	v_pk_mul_f32 v[60:61], v[16:17], v[60:61]
	v_pk_mul_f32 v[62:63], v[18:19], v[62:63]
	global_store_dwordx4 v[78:79], v[60:63], off
	s_nop 1
	v_pk_mul_f32 v[60:61], v[96:97], v[84:85] op_sel_hi:[1,0]
	v_pk_mul_f32 v[62:63], v[98:99], v[84:85] op_sel_hi:[1,0]
	v_pk_mul_f32 v[60:61], v[20:21], v[60:61]
	v_pk_mul_f32 v[62:63], v[22:23], v[62:63]
	global_store_dwordx4 v[80:81], v[60:63], off
	s_nop 1
	v_pk_mul_f32 v[60:61], v[102:103], v[84:85] op_sel_hi:[1,0]
	v_pk_mul_f32 v[62:63], v[104:105], v[84:85] op_sel_hi:[1,0]
	v_pk_mul_f32 v[60:61], v[24:25], v[60:61]
	v_pk_mul_f32 v[62:63], v[26:27], v[62:63]
	global_store_dwordx4 v[82:83], v[60:63], off
	s_nop 1
	v_pk_mul_f32 v[60:61], v[106:107], v[84:85] op_sel_hi:[1,0]
	v_pk_mul_f32 v[62:63], v[108:109], v[84:85] op_sel_hi:[1,0]
	v_pk_mul_f32 v[60:61], v[28:29], v[60:61]
	v_pk_mul_f32 v[62:63], v[30:31], v[62:63]
	global_store_dwordx4 v[50:51], v[60:63], off
	s_andn2_b64 exec, exec, s[0:1]
	s_cbranch_execnz .LBB0_566
